# attention first-unit n->s register copies moved from the post-MFMA tail into PV MFMA gaps
# speedup vs baseline: 1.0007x; 1.0007x over previous
; #define LAS __attribute__((address_space(3)))
; #define MFMA32(a, b, c) __builtin_amdgcn_mfma_f32_32x32x16_bf16((a), (b), (c), 0, 0, 0)
; DI bf16x8 pack8(const f32x16& x, int s) { u32x4 p; p.x = pk2(x[8 * s], x[8 * s + 1]); p.y = pk2(x[8 * s + 2], x[8 * s + 3]); p.z = pk2(x[8 * s + 4], x[8 * s + 5]); p.w = pk2(x[8 * s + 6], x[8 * s + 7]); return __builtin_bit_cast(bf16x8, p); }
; #define ATT_STOREK(buf) do { _Pragma("unroll") for (int i = 0; i < 3; ++i) *(LAS u32x4*)(lds + (buf) * ATT_KB + klo + 128 * i) = kreg[i]; } while (0)
; #define ATT_STOREV(buf) do { _Pragma("unroll") for (int i = 0; i < 2; ++i) *(LAS u32x4*)(lds + (buf) * ATT_VB + vlo + 64 * i) = vreg[i]; } while (0)
; DI void attn_unit(LAS unsigned char* lds, const bf16_t* __restrict__ Q, const bf16_t* __restrict__ Kg, const bf16_t* __restrict__ VT, bf16_t* __restrict__ MIX, int b, int h, int c0, int nq, int desc) {
;     ...
;       float ps = 0.f;
; #pragma unroll
;       for (int i = 0; i < 16; ++i) ps += s0[i] + s1[i];
;       lrun += ps;
;       bf16x8 pf[4]; pf[0] = pack8(s0, 0); pf[1] = pack8(s0, 1); pf[2] = pack8(s1, 0); pf[3] = pack8(s1, 1);
;       const LAS unsigned char* vb = lds + 2 * ATT_KB + buf * ATT_VB + r31 * HROW + 16 * hh;
; #pragma unroll
;       for (int kk = 0; kk < 4; ++kk)
; #pragma unroll
;         for (int d = 0; d < 4; ++d) { const bf16x8 a = *(const LAS bf16x8*)(vb + d * 32 * HROW + 32 * kk); O[d] = MFMA32(a, pf[kk], O[d]); }
;     ...
;     if (t + 2 < nt) ATT_STOREK(buf);
;     if (t + 1 < nt) ATT_STOREV(buf ^ 1);
;     __syncthreads();
;     s0 = n0; s1 = n1;
.Lnok_LBB0_551:
	s_waitcnt lgkmcnt(3)
	v_mfma_f32_32x32x16_bf16 v[2:17], v[234:237], v[82:85], v[2:17]
	ds_read_b128 v[234:237], v223 offset:65056
	v_add_f32_e32 v238, v238, v239
	v_add_f32_e32 v240, v240, v241
	v_mov_b64_e32 v[86:87], v[102:103]
	v_mov_b64_e32 v[94:95], v[110:111]
	s_waitcnt lgkmcnt(3)
	v_mfma_f32_32x32x16_bf16 v[50:65], v[212:215], v[90:93], v[50:65]
	ds_read_b128 v[212:215], v223 offset:51264
	v_add_f32_e32 v0, v238, v240
	v_mov_b64_e32 v[70:71], v[118:119]
	v_mov_b64_e32 v[78:79], v[126:127]
	s_waitcnt lgkmcnt(3)
	v_mfma_f32_32x32x16_bf16 v[34:49], v[218:221], v[90:93], v[34:49]
	ds_read_b128 v[218:221], v223 offset:55872
	v_add_f32_e32 v210, v210, v0
	v_mov_b64_e32 v[88:89], v[104:105]
	v_mov_b64_e32 v[96:97], v[112:113]
	s_waitcnt lgkmcnt(3)
	v_mfma_f32_32x32x16_bf16 v[18:33], v[230:233], v[90:93], v[18:33]
	ds_read_b128 v[230:233], v223 offset:60480
	s_xor_b32 s98, s12, 1
	s_mulk_i32 s98, 0x4800
	v_add_u32_e32 v229, s98, v206
	s_waitcnt vmcnt(0)
	ds_write_b128 v229, v[190:193] offset:51200
	ds_write_b128 v229, v[194:197] offset:51264
	s_waitcnt lgkmcnt(3)
	v_mfma_f32_32x32x16_bf16 v[2:17], v[234:237], v[90:93], v[2:17]
	ds_read_b128 v[234:237], v223 offset:65088
	v_mov_b64_e32 v[72:73], v[120:121]
	v_mov_b64_e32 v[80:81], v[128:129]
	s_waitcnt lgkmcnt(3)
	v_mfma_f32_32x32x16_bf16 v[50:65], v[212:215], v[66:69], v[50:65]
	ds_read_b128 v[212:215], v223 offset:51296
	v_mov_b64_e32 v[82:83], v[98:99]
	v_mov_b64_e32 v[84:85], v[100:101]
	s_waitcnt lgkmcnt(3)
	v_mfma_f32_32x32x16_bf16 v[34:49], v[218:221], v[66:69], v[34:49]
	ds_read_b128 v[218:221], v223 offset:55904
	v_mov_b64_e32 v[90:91], v[106:107]
	v_mov_b64_e32 v[92:93], v[108:109]
	s_waitcnt lgkmcnt(3)
	v_mfma_f32_32x32x16_bf16 v[18:33], v[230:233], v[66:69], v[18:33]
	ds_read_b128 v[230:233], v223 offset:60512
	s_waitcnt lgkmcnt(3)
	v_mfma_f32_32x32x16_bf16 v[2:17], v[234:237], v[66:69], v[2:17]
	ds_read_b128 v[234:237], v223 offset:65120
	s_waitcnt lgkmcnt(3)
	v_mfma_f32_32x32x16_bf16 v[50:65], v[212:215], v[74:77], v[50:65]
	v_mov_b64_e32 v[66:67], v[114:115]
	v_mov_b64_e32 v[68:69], v[116:117]
	s_waitcnt lgkmcnt(2)
	v_mfma_f32_32x32x16_bf16 v[34:49], v[218:221], v[74:77], v[34:49]
	s_waitcnt lgkmcnt(1)
	v_mfma_f32_32x32x16_bf16 v[18:33], v[230:233], v[74:77], v[18:33]
	s_waitcnt lgkmcnt(0)
	v_mfma_f32_32x32x16_bf16 v[2:17], v[234:237], v[74:77], v[2:17]
	v_mov_b64_e32 v[74:75], v[122:123]
	v_mov_b64_e32 v[76:77], v[124:125]
	s_or_b64 exec, exec, s[30:31]
	s_branch .LBB0_554
	s_andn2_b64 vcc, exec, s[26:27]
	s_cbranch_vccz .LBB0_560
